# phase 14: nt (streaming) hint on the sixteen final-output stores of LN2
# baseline (speedup 1.0000x reference)
.LBB0_1619:
	v_ashrrev_i32_e32 v5, 31, v4
	v_lshlrev_b64 v[0:1], 11, v[4:5]
	v_add_u32_e32 v36, 1, v4
	v_lshl_add_u64 v[20:21], v[6:7], 0, v[0:1]
	v_ashrrev_i32_e32 v37, 31, v36
	global_load_dwordx4 v[0:3], v[20:21], off
	global_load_dwordx4 v[16:19], v[20:21], off offset:1024
	v_lshlrev_b64 v[20:21], 11, v[36:37]
	v_lshl_add_u64 v[28:29], v[6:7], 0, v[20:21]
	global_load_dwordx4 v[20:23], v[28:29], off
	global_load_dwordx4 v[24:27], v[28:29], off offset:1024
	global_load_dwordx4 v[54:57], v[8:9], off offset:16
	global_load_dwordx4 v[58:61], v[8:9], off
	global_load_dwordx4 v[62:65], v[10:11], off offset:16
	global_load_dwordx4 v[66:69], v[10:11], off
	v_lshlrev_b64 v[36:37], 12, v[36:37]
	v_lshl_add_u64 v[36:37], v[12:13], 0, v[36:37]
	s_waitcnt vmcnt(0)
	v_lshlrev_b32_e32 v30, 16, v0
	v_and_b32_e32 v31, 0xffff0000, v0
	v_add_f32_e32 v40, 0, v30
	v_lshlrev_b32_e32 v70, 16, v20
	v_lshlrev_b32_e32 v0, 16, v1
	v_and_b32_e32 v71, 0xffff0000, v20
	v_add_f32_e32 v40, v40, v31
	v_add_f32_e32 v41, 0, v70
	v_and_b32_e32 v1, 0xffff0000, v1
	v_lshlrev_b32_e32 v20, 16, v21
	v_add_f32_e32 v40, v40, v0
	v_add_f32_e32 v41, v41, v71
	v_lshlrev_b32_e32 v28, 16, v2
	v_and_b32_e32 v21, 0xffff0000, v21
	v_add_f32_e32 v40, v40, v1
	v_add_f32_e32 v41, v41, v20
	v_and_b32_e32 v29, 0xffff0000, v2
	v_lshlrev_b32_e32 v38, 16, v22
	v_add_f32_e32 v40, v40, v28
	v_add_f32_e32 v41, v41, v21
	v_lshlrev_b32_e32 v2, 16, v3
	v_and_b32_e32 v39, 0xffff0000, v22
	v_add_f32_e32 v40, v40, v29
	v_add_f32_e32 v41, v41, v38
	v_and_b32_e32 v3, 0xffff0000, v3
	v_lshlrev_b32_e32 v22, 16, v23
	v_add_f32_e32 v40, v40, v2
	v_add_f32_e32 v41, v41, v39
	v_lshlrev_b32_e32 v34, 16, v16
	v_and_b32_e32 v23, 0xffff0000, v23
	v_add_f32_e32 v40, v40, v3
	v_add_f32_e32 v41, v41, v22
	v_and_b32_e32 v35, 0xffff0000, v16
	v_lshlrev_b32_e32 v74, 16, v24
	v_add_f32_e32 v40, v40, v34
	v_add_f32_e32 v41, v41, v23
	v_lshlrev_b32_e32 v16, 16, v17
	v_and_b32_e32 v75, 0xffff0000, v24
	v_add_f32_e32 v40, v40, v35
	v_add_f32_e32 v41, v41, v74
	v_and_b32_e32 v17, 0xffff0000, v17
	v_lshlrev_b32_e32 v24, 16, v25
	v_add_f32_e32 v40, v40, v16
	v_add_f32_e32 v41, v41, v75
	v_lshlrev_b32_e32 v32, 16, v18
	v_and_b32_e32 v25, 0xffff0000, v25
	v_add_f32_e32 v40, v40, v17
	v_add_f32_e32 v41, v41, v24
	v_and_b32_e32 v33, 0xffff0000, v18
	v_lshlrev_b32_e32 v72, 16, v26
	v_add_f32_e32 v40, v40, v32
	v_add_f32_e32 v41, v41, v25
	v_lshlrev_b32_e32 v18, 16, v19
	v_and_b32_e32 v73, 0xffff0000, v26
	v_add_f32_e32 v40, v40, v33
	v_add_f32_e32 v41, v41, v72
	v_and_b32_e32 v19, 0xffff0000, v19
	v_lshlrev_b32_e32 v26, 16, v27
	v_add_f32_e32 v40, v40, v18
	v_add_f32_e32 v41, v41, v73
	v_and_b32_e32 v27, 0xffff0000, v27
	v_add_f32_e32 v40, v40, v19
	v_add_f32_e32 v41, v41, v26
	ds_bpermute_b32 v42, v48, v40
	v_add_f32_e32 v41, v41, v27
	ds_bpermute_b32 v43, v48, v41
	s_waitcnt lgkmcnt(1)
	v_add_f32_e32 v40, v40, v42
	ds_bpermute_b32 v42, v49, v40
	s_waitcnt lgkmcnt(1)
	v_add_f32_e32 v41, v41, v43
	ds_bpermute_b32 v43, v49, v41
	s_waitcnt lgkmcnt(1)
	v_add_f32_e32 v40, v40, v42
	ds_bpermute_b32 v42, v50, v40
	s_waitcnt lgkmcnt(1)
	v_add_f32_e32 v41, v41, v43
	ds_bpermute_b32 v43, v50, v41
	s_waitcnt lgkmcnt(1)
	v_add_f32_e32 v40, v40, v42
	ds_bpermute_b32 v42, v51, v40
	s_waitcnt lgkmcnt(1)
	v_add_f32_e32 v41, v41, v43
	ds_bpermute_b32 v43, v51, v41
	s_waitcnt lgkmcnt(1)
	v_add_f32_e32 v40, v40, v42
	ds_bpermute_b32 v42, v52, v40
	s_waitcnt lgkmcnt(1)
	v_add_f32_e32 v41, v41, v43
	ds_bpermute_b32 v43, v52, v41
	s_waitcnt lgkmcnt(1)
	v_add_f32_e32 v40, v40, v42
	ds_bpermute_b32 v42, v53, v40
	s_waitcnt lgkmcnt(1)
	v_add_f32_e32 v41, v41, v43
	ds_bpermute_b32 v43, v53, v41
	s_waitcnt lgkmcnt(1)
	v_add_f32_e32 v40, v40, v42
	v_mul_f32_e32 v46, 0x3a800000, v40
	s_waitcnt lgkmcnt(0)
	v_add_f32_e32 v76, v41, v43
	v_pk_add_f32 v[84:85], v[0:1], v[46:47] op_sel_hi:[1,0] neg_lo:[0,1] neg_hi:[0,1]
	v_mul_f32_e32 v0, 0x3a800000, v76
	v_pk_add_f32 v[82:83], v[30:31], v[46:47] op_sel_hi:[1,0] neg_lo:[0,1] neg_hi:[0,1]
	v_pk_add_f32 v[86:87], v[28:29], v[46:47] op_sel_hi:[1,0] neg_lo:[0,1] neg_hi:[0,1]
	v_pk_add_f32 v[28:29], v[70:71], v[0:1] op_sel_hi:[1,0] neg_lo:[0,1] neg_hi:[0,1]
	v_mov_b32_e32 v77, v83
	v_mov_b32_e32 v76, v29
	v_mov_b32_e32 v71, v82
	v_pk_add_f32 v[30:31], v[20:21], v[0:1] op_sel_hi:[1,0] neg_lo:[0,1] neg_hi:[0,1]
	v_mov_b32_e32 v70, v28
	v_pk_mul_f32 v[76:77], v[76:77], v[76:77]
	v_mov_b32_e32 v79, v84
	v_mov_b32_e32 v78, v30
	v_pk_fma_f32 v[70:71], v[70:71], v[70:71], v[76:77]
	v_pk_add_f32 v[40:41], v[34:35], v[46:47] op_sel_hi:[1,0] neg_lo:[0,1] neg_hi:[0,1]
	v_pk_add_f32 v[42:43], v[32:33], v[46:47] op_sel_hi:[1,0] neg_lo:[0,1] neg_hi:[0,1]
	v_pk_add_f32 v[32:33], v[38:39], v[0:1] op_sel_hi:[1,0] neg_lo:[0,1] neg_hi:[0,1]
	v_pk_add_f32 v[34:35], v[22:23], v[0:1] op_sel_hi:[1,0] neg_lo:[0,1] neg_hi:[0,1]
	v_pk_add_f32 v[22:23], v[24:25], v[0:1] op_sel_hi:[1,0] neg_lo:[0,1] neg_hi:[0,1]
	v_mov_b32_e32 v25, v85
	v_mov_b32_e32 v24, v31
	v_pk_fma_f32 v[70:71], v[78:79], v[78:79], v[70:71]
	v_mov_b32_e32 v39, v86
	v_mov_b32_e32 v38, v32
	v_pk_fma_f32 v[24:25], v[24:25], v[24:25], v[70:71]
	v_pk_add_f32 v[88:89], v[2:3], v[46:47] op_sel_hi:[1,0] neg_lo:[0,1] neg_hi:[0,1]
	v_pk_add_f32 v[20:21], v[72:73], v[0:1] op_sel_hi:[1,0] neg_lo:[0,1] neg_hi:[0,1]
	v_mov_b32_e32 v73, v87
	v_mov_b32_e32 v72, v33
	v_pk_fma_f32 v[24:25], v[38:39], v[38:39], v[24:25]
	v_pk_add_f32 v[44:45], v[16:17], v[46:47] op_sel_hi:[1,0] neg_lo:[0,1] neg_hi:[0,1]
	v_pk_add_f32 v[46:47], v[18:19], v[46:47] op_sel_hi:[1,0] neg_lo:[0,1] neg_hi:[0,1]
	v_pk_add_f32 v[18:19], v[74:75], v[0:1] op_sel_hi:[1,0] neg_lo:[0,1] neg_hi:[0,1]
	v_mov_b32_e32 v75, v88
	v_mov_b32_e32 v74, v34
	v_pk_fma_f32 v[24:25], v[72:73], v[72:73], v[24:25]
	v_mov_b32_e32 v81, v89
	v_mov_b32_e32 v80, v35
	v_pk_fma_f32 v[24:25], v[74:75], v[74:75], v[24:25]
	v_mov_b32_e32 v92, v18
	v_pk_fma_f32 v[24:25], v[80:81], v[80:81], v[24:25]
	v_mov_b32_e32 v93, v40
	v_pk_fma_f32 v[24:25], v[92:93], v[92:93], v[24:25]
	v_mov_b32_e32 v38, v19
	v_mov_b32_e32 v39, v41
	v_pk_fma_f32 v[24:25], v[38:39], v[38:39], v[24:25]
	v_mov_b32_e32 v38, v22
	v_mov_b32_e32 v39, v44
	v_pk_mul_f32 v[2:3], v[42:43], v[42:43]
	v_pk_mul_f32 v[90:91], v[20:21], v[20:21]
	v_pk_fma_f32 v[24:25], v[38:39], v[38:39], v[24:25]
	v_mov_b32_e32 v38, v23
	v_mov_b32_e32 v39, v45
	v_pk_fma_f32 v[24:25], v[38:39], v[38:39], v[24:25]
	v_mov_b32_e32 v38, v90
	v_mov_b32_e32 v39, v2
	v_pk_add_f32 v[26:27], v[26:27], v[0:1] op_sel_hi:[1,0] neg_lo:[0,1] neg_hi:[0,1]
	v_pk_mul_f32 v[16:17], v[46:47], v[46:47]
	v_pk_add_f32 v[24:25], v[38:39], v[24:25]
	v_pk_mul_f32 v[0:1], v[26:27], v[26:27]
	v_mov_b32_e32 v2, v91
	v_pk_add_f32 v[2:3], v[2:3], v[24:25]
	v_mov_b32_e32 v24, v0
	v_mov_b32_e32 v25, v16
	v_pk_add_f32 v[2:3], v[24:25], v[2:3]
	v_mov_b32_e32 v16, v1
	v_pk_add_f32 v[0:1], v[16:17], v[2:3]
	ds_bpermute_b32 v3, v48, v1
	ds_bpermute_b32 v2, v48, v0
	v_add_u32_e32 v24, 2, v4
	v_ashrrev_i32_e32 v25, 31, v24
	v_lshlrev_b64 v[16:17], 11, v[24:25]
	v_lshl_add_u64 v[16:17], v[6:7], 0, v[16:17]
	s_waitcnt lgkmcnt(0)
	v_pk_add_f32 v[0:1], v[0:1], v[2:3]
	ds_bpermute_b32 v3, v49, v1
	ds_bpermute_b32 v2, v49, v0
	global_load_dwordx4 v[70:73], v[16:17], off
	global_load_dwordx4 v[74:77], v[16:17], off offset:1024
	v_add_u32_e32 v16, 3, v4
	v_ashrrev_i32_e32 v17, 31, v16
	v_lshlrev_b64 v[38:39], 11, v[16:17]
	s_waitcnt lgkmcnt(0)
	v_pk_add_f32 v[0:1], v[0:1], v[2:3]
	ds_bpermute_b32 v3, v50, v1
	ds_bpermute_b32 v2, v50, v0
	v_lshl_add_u64 v[90:91], v[6:7], 0, v[38:39]
	v_lshlrev_b64 v[16:17], 12, v[16:17]
	s_waitcnt lgkmcnt(0)
	v_pk_add_f32 v[0:1], v[0:1], v[2:3]
	ds_bpermute_b32 v3, v51, v1
	ds_bpermute_b32 v2, v51, v0
	s_waitcnt lgkmcnt(0)
	v_pk_add_f32 v[0:1], v[0:1], v[2:3]
	ds_bpermute_b32 v3, v52, v1
	ds_bpermute_b32 v2, v52, v0
	s_waitcnt lgkmcnt(0)
	v_pk_add_f32 v[0:1], v[0:1], v[2:3]
	ds_bpermute_b32 v3, v53, v1
	ds_bpermute_b32 v2, v53, v0
	s_waitcnt lgkmcnt(0)
	v_pk_add_f32 v[0:1], v[0:1], v[2:3]
	s_nop 0
	v_pk_fma_f32 v[38:39], v[0:1], s[2:3], v[14:15] op_sel_hi:[1,0,0]
	s_nop 0
	v_mul_f32_e32 v0, 0x4b800000, v39
	v_cmp_gt_f32_e32 vcc, s4, v39
	s_nop 1
	v_cndmask_b32_e32 v0, v39, v0, vcc
	v_rsq_f32_e32 v39, v0
	global_load_dwordx4 v[78:81], v[90:91], off
	global_load_dwordx4 v[0:3], v[90:91], off offset:1024
	v_lshlrev_b64 v[90:91], 12, v[4:5]
	v_lshl_add_u64 v[90:91], v[12:13], 0, v[90:91]
	v_mul_f32_e32 v5, 0x45800000, v39
	v_cndmask_b32_e32 v92, v39, v5, vcc
	v_pk_mul_f32 v[82:83], v[82:83], v[92:93] op_sel_hi:[1,0]
	v_pk_mul_f32 v[84:85], v[84:85], v[92:93] op_sel_hi:[1,0]
	v_pk_fma_f32 v[58:59], v[58:59], v[82:83], v[66:67]
	v_pk_fma_f32 v[60:61], v[60:61], v[84:85], v[68:69]
	v_pk_mul_f32 v[66:67], v[86:87], v[92:93] op_sel_hi:[1,0]
	v_pk_mul_f32 v[68:69], v[88:89], v[92:93] op_sel_hi:[1,0]
	v_pk_fma_f32 v[54:55], v[54:55], v[66:67], v[62:63]
	v_pk_fma_f32 v[56:57], v[56:57], v[68:69], v[64:65]
	global_store_dwordx4 v[90:91], v[58:61], off nt
	global_store_dwordx4 v[90:91], v[54:57], off offset:16 nt
	global_load_dwordx4 v[54:57], v[10:11], off offset:2048
	s_nop 0
	global_load_dwordx4 v[58:61], v[8:9], off offset:2048
	global_load_dwordx4 v[62:65], v[8:9], off offset:2064
	global_load_dwordx4 v[66:69], v[10:11], off offset:2064
	v_pk_mul_f32 v[44:45], v[44:45], v[92:93] op_sel_hi:[1,0]
	v_pk_mul_f32 v[40:41], v[40:41], v[92:93] op_sel_hi:[1,0]
	v_pk_mul_f32 v[46:47], v[46:47], v[92:93] op_sel_hi:[1,0]
	v_pk_mul_f32 v[84:85], v[42:43], v[92:93] op_sel_hi:[1,0]
	v_cmp_gt_f32_e32 vcc, s4, v38
	v_add_u32_e32 v4, s3, v4
	s_waitcnt vmcnt(9)
	v_lshlrev_b32_e32 v82, 16, v72
	v_and_b32_e32 v83, 0xffff0000, v72
	s_waitcnt vmcnt(8)
	v_lshlrev_b32_e32 v72, 16, v74
	s_waitcnt vmcnt(6)
	v_lshlrev_b32_e32 v92, 16, v1
	v_and_b32_e32 v93, 0xffff0000, v1
	v_lshlrev_b32_e32 v86, 16, v2
	v_and_b32_e32 v87, 0xffff0000, v2
	v_lshlrev_b32_e32 v88, 16, v3
	v_and_b32_e32 v89, 0xffff0000, v3
	s_waitcnt vmcnt(2)
	v_pk_fma_f32 v[40:41], v[58:59], v[40:41], v[54:55]
	v_pk_fma_f32 v[42:43], v[60:61], v[44:45], v[56:57]
	s_waitcnt vmcnt(0)
	v_pk_fma_f32 v[44:45], v[62:63], v[84:85], v[66:67]
	v_pk_fma_f32 v[46:47], v[64:65], v[46:47], v[68:69]
	global_store_dwordx4 v[90:91], v[40:43], off offset:2048 nt
	global_store_dwordx4 v[90:91], v[44:47], off offset:2064 nt
	global_load_dwordx4 v[40:43], v[8:9], off offset:16
	s_nop 0
	global_load_dwordx4 v[44:47], v[8:9], off
	global_load_dwordx4 v[54:57], v[10:11], off offset:16
	global_load_dwordx4 v[58:61], v[10:11], off
	v_lshlrev_b32_e32 v64, 16, v70
	v_and_b32_e32 v65, 0xffff0000, v70
	v_lshlrev_b32_e32 v90, 16, v0
	v_and_b32_e32 v91, 0xffff0000, v0
	v_add_f32_e32 v0, 0, v64
	v_lshlrev_b32_e32 v66, 16, v71
	v_add_f32_e32 v0, v0, v65
	v_and_b32_e32 v67, 0xffff0000, v71
	v_add_f32_e32 v0, v0, v66
	v_add_f32_e32 v0, v0, v67
	v_add_f32_e32 v0, v0, v82
	v_lshlrev_b32_e32 v62, 16, v73
	v_lshlrev_b32_e32 v84, 16, v78
	v_add_f32_e32 v0, v0, v83
	v_and_b32_e32 v63, 0xffff0000, v73
	v_and_b32_e32 v85, 0xffff0000, v78
	v_add_f32_e32 v1, 0, v84
	v_add_f32_e32 v0, v0, v62
	v_lshlrev_b32_e32 v78, 16, v79
	v_add_f32_e32 v1, v1, v85
	v_add_f32_e32 v0, v0, v63
	v_and_b32_e32 v73, 0xffff0000, v74
	v_and_b32_e32 v79, 0xffff0000, v79
	v_add_f32_e32 v1, v1, v78
	v_add_f32_e32 v0, v0, v72
	v_lshlrev_b32_e32 v68, 16, v76
	v_and_b32_e32 v69, 0xffff0000, v76
	v_lshlrev_b32_e32 v74, 16, v75
	v_lshlrev_b32_e32 v76, 16, v80
	v_add_f32_e32 v1, v1, v79
	v_add_f32_e32 v0, v0, v73
	v_lshlrev_b32_e32 v70, 16, v77
	v_and_b32_e32 v71, 0xffff0000, v77
	v_and_b32_e32 v75, 0xffff0000, v75
	v_and_b32_e32 v77, 0xffff0000, v80
	v_add_f32_e32 v1, v1, v76
	v_add_f32_e32 v0, v0, v74
	v_lshlrev_b32_e32 v80, 16, v81
	v_add_f32_e32 v1, v1, v77
	v_add_f32_e32 v0, v0, v75
	v_and_b32_e32 v81, 0xffff0000, v81
	v_add_f32_e32 v1, v1, v80
	v_add_f32_e32 v0, v0, v68
	v_add_f32_e32 v1, v1, v81
	v_add_f32_e32 v0, v0, v69
	v_add_f32_e32 v1, v1, v90
	v_add_f32_e32 v0, v0, v70
	v_add_f32_e32 v1, v1, v91
	v_add_f32_e32 v0, v0, v71
	v_add_f32_e32 v1, v1, v92
	ds_bpermute_b32 v2, v48, v0
	v_add_f32_e32 v1, v1, v93
	v_add_f32_e32 v1, v1, v86
	v_add_f32_e32 v1, v1, v87
	v_add_f32_e32 v1, v1, v88
	v_add_f32_e32 v1, v1, v89
	s_waitcnt lgkmcnt(0)
	v_add_f32_e32 v5, v0, v2
	v_mul_f32_e32 v0, 0x4b800000, v38
	ds_bpermute_b32 v3, v48, v1
	v_cndmask_b32_e32 v0, v38, v0, vcc
	v_rsq_f32_e32 v0, v0
	ds_bpermute_b32 v96, v49, v5
	s_waitcnt lgkmcnt(1)
	v_add_f32_e32 v95, v1, v3
	v_mul_f32_e32 v1, 0x45800000, v0
	v_cndmask_b32_e32 v94, v0, v1, vcc
	v_pk_mul_f32 v[2:3], v[30:31], v[94:95] op_sel_hi:[1,0]
	v_pk_mul_f32 v[0:1], v[28:29], v[94:95] op_sel_hi:[1,0]
	v_pk_mul_f32 v[30:31], v[34:35], v[94:95] op_sel_hi:[1,0]
	v_pk_mul_f32 v[28:29], v[32:33], v[94:95] op_sel_hi:[1,0]
	ds_bpermute_b32 v97, v49, v95
	v_pk_mul_f32 v[22:23], v[22:23], v[94:95] op_sel_hi:[1,0]
	v_pk_mul_f32 v[18:19], v[18:19], v[94:95] op_sel_hi:[1,0]
	v_pk_mul_f32 v[26:27], v[26:27], v[94:95] op_sel_hi:[1,0]
	s_waitcnt vmcnt(1)
	v_pk_fma_f32 v[28:29], v[40:41], v[28:29], v[54:55]
	s_waitcnt vmcnt(0)
	v_pk_fma_f32 v[0:1], v[44:45], v[0:1], v[58:59]
	v_pk_fma_f32 v[2:3], v[46:47], v[2:3], v[60:61]
	v_pk_fma_f32 v[30:31], v[42:43], v[30:31], v[56:57]
	global_store_dwordx4 v[36:37], v[0:3], off nt
	global_store_dwordx4 v[36:37], v[28:31], off offset:16 nt
	global_load_dwordx4 v[32:35], v[8:9], off offset:2064
	global_load_dwordx4 v[38:41], v[8:9], off offset:2048
	global_load_dwordx4 v[42:45], v[10:11], off offset:2064
	global_load_dwordx4 v[54:57], v[10:11], off offset:2048
	s_waitcnt lgkmcnt(1)
	v_add_f32_e32 v0, v5, v96
	s_waitcnt lgkmcnt(0)
	v_add_f32_e32 v1, v95, v97
	ds_bpermute_b32 v2, v50, v0
	ds_bpermute_b32 v3, v50, v1
	v_pk_mul_f32 v[94:95], v[20:21], v[94:95] op_sel_hi:[1,0]
	s_waitcnt lgkmcnt(1)
	v_add_f32_e32 v0, v0, v2
	s_waitcnt lgkmcnt(0)
	v_add_f32_e32 v1, v1, v3
	ds_bpermute_b32 v2, v51, v0
	ds_bpermute_b32 v3, v51, v1
	s_waitcnt lgkmcnt(1)
	v_add_f32_e32 v0, v0, v2
	s_waitcnt lgkmcnt(0)
	v_add_f32_e32 v1, v1, v3
	ds_bpermute_b32 v2, v52, v0
	ds_bpermute_b32 v3, v52, v1
	s_waitcnt lgkmcnt(1)
	v_add_f32_e32 v0, v0, v2
	s_waitcnt lgkmcnt(0)
	v_add_f32_e32 v1, v1, v3
	ds_bpermute_b32 v2, v53, v0
	ds_bpermute_b32 v3, v53, v1
	s_waitcnt lgkmcnt(1)
	v_add_f32_e32 v0, v0, v2
	s_waitcnt lgkmcnt(0)
	v_add_f32_e32 v1, v1, v3
	v_mul_f32_e32 v0, 0x3a800000, v0
	v_mul_f32_e32 v30, 0x3a800000, v1
	v_pk_add_f32 v[46:47], v[64:65], v[0:1] op_sel_hi:[1,0] neg_lo:[0,1] neg_hi:[0,1]
	v_pk_add_f32 v[64:65], v[72:73], v[0:1] op_sel_hi:[1,0] neg_lo:[0,1] neg_hi:[0,1]
	v_pk_add_f32 v[72:73], v[84:85], v[30:31] op_sel_hi:[1,0] neg_lo:[0,1] neg_hi:[0,1]
	v_pk_add_f32 v[58:59], v[66:67], v[0:1] op_sel_hi:[1,0] neg_lo:[0,1] neg_hi:[0,1]
	v_pk_add_f32 v[60:61], v[82:83], v[0:1] op_sel_hi:[1,0] neg_lo:[0,1] neg_hi:[0,1]
	v_pk_add_f32 v[62:63], v[62:63], v[0:1] op_sel_hi:[1,0] neg_lo:[0,1] neg_hi:[0,1]
	v_pk_add_f32 v[66:67], v[74:75], v[0:1] op_sel_hi:[1,0] neg_lo:[0,1] neg_hi:[0,1]
	v_pk_add_f32 v[68:69], v[68:69], v[0:1] op_sel_hi:[1,0] neg_lo:[0,1] neg_hi:[0,1]
	v_pk_add_f32 v[70:71], v[70:71], v[0:1] op_sel_hi:[1,0] neg_lo:[0,1] neg_hi:[0,1]
	v_pk_add_f32 v[74:75], v[78:79], v[30:31] op_sel_hi:[1,0] neg_lo:[0,1] neg_hi:[0,1]
	v_pk_add_f32 v[76:77], v[76:77], v[30:31] op_sel_hi:[1,0] neg_lo:[0,1] neg_hi:[0,1]
	v_pk_add_f32 v[78:79], v[80:81], v[30:31] op_sel_hi:[1,0] neg_lo:[0,1] neg_hi:[0,1]
	v_pk_add_f32 v[0:1], v[90:91], v[30:31] op_sel_hi:[1,0] neg_lo:[0,1] neg_hi:[0,1]
	v_pk_add_f32 v[28:29], v[92:93], v[30:31] op_sel_hi:[1,0] neg_lo:[0,1] neg_hi:[0,1]
	v_pk_add_f32 v[2:3], v[86:87], v[30:31] op_sel_hi:[1,0] neg_lo:[0,1] neg_hi:[0,1]
	v_pk_add_f32 v[30:31], v[88:89], v[30:31] op_sel_hi:[1,0] neg_lo:[0,1] neg_hi:[0,1]
	v_mov_b32_e32 v86, v73
	v_mov_b32_e32 v87, v47
	v_pk_mul_f32 v[82:83], v[70:71], v[70:71]
	v_mov_b32_e32 v84, v72
	v_mov_b32_e32 v85, v46
	v_mov_b32_e32 v88, v74
	v_mov_b32_e32 v89, v58
	v_mov_b32_e32 v92, v75
	v_mov_b32_e32 v93, v59
	v_mov_b32_e32 v96, v76
	v_mov_b32_e32 v97, v60
	v_mov_b32_e32 v98, v77
	v_mov_b32_e32 v99, v61
	v_mov_b32_e32 v100, v78
	v_mov_b32_e32 v101, v62
	v_mov_b32_e32 v102, v79
	v_mov_b32_e32 v103, v63
	v_mov_b32_e32 v104, v0
	v_mov_b32_e32 v105, v64
	v_mov_b32_e32 v106, v1
	v_mov_b32_e32 v107, v65
	v_mov_b32_e32 v108, v28
	v_mov_b32_e32 v109, v66
	v_pk_mul_f32 v[80:81], v[68:69], v[68:69]
	v_pk_mul_f32 v[90:91], v[2:3], v[2:3]
	v_mov_b32_e32 v110, v29
	v_mov_b32_e32 v111, v67
	s_waitcnt vmcnt(1)
	v_pk_fma_f32 v[32:33], v[32:33], v[94:95], v[42:43]
	s_waitcnt vmcnt(0)
	v_pk_fma_f32 v[18:19], v[38:39], v[18:19], v[54:55]
	v_pk_fma_f32 v[20:21], v[40:41], v[22:23], v[56:57]
	v_pk_fma_f32 v[34:35], v[34:35], v[26:27], v[44:45]
	global_store_dwordx4 v[36:37], v[18:21], off offset:2048 nt
	global_store_dwordx4 v[36:37], v[32:35], off offset:2064 nt
	global_load_dwordx4 v[18:21], v[8:9], off offset:16
	s_nop 0
	global_load_dwordx4 v[32:35], v[8:9], off
	global_load_dwordx4 v[36:39], v[10:11], off offset:16
	global_load_dwordx4 v[40:43], v[10:11], off
	v_pk_mul_f32 v[22:23], v[30:31], v[30:31]
	v_pk_mul_f32 v[26:27], v[86:87], v[86:87]
	v_mov_b32_e32 v54, v22
	v_mov_b32_e32 v55, v82
	v_mov_b32_e32 v82, v23
	v_pk_fma_f32 v[22:23], v[84:85], v[84:85], v[26:27]
	v_mov_b32_e32 v44, v90
	v_pk_fma_f32 v[22:23], v[88:89], v[88:89], v[22:23]
	v_mov_b32_e32 v45, v80
	v_pk_fma_f32 v[22:23], v[92:93], v[92:93], v[22:23]
	v_mov_b32_e32 v80, v91
	v_pk_fma_f32 v[22:23], v[96:97], v[96:97], v[22:23]
	s_nop 0
	v_pk_fma_f32 v[22:23], v[98:99], v[98:99], v[22:23]
	s_nop 0
	v_pk_fma_f32 v[22:23], v[100:101], v[100:101], v[22:23]
	s_nop 0
	v_pk_fma_f32 v[22:23], v[102:103], v[102:103], v[22:23]
	s_nop 0
	v_pk_fma_f32 v[22:23], v[104:105], v[104:105], v[22:23]
	s_nop 0
	v_pk_fma_f32 v[22:23], v[106:107], v[106:107], v[22:23]
	s_nop 0
	v_pk_fma_f32 v[22:23], v[108:109], v[108:109], v[22:23]
	s_nop 0
	v_pk_fma_f32 v[22:23], v[110:111], v[110:111], v[22:23]
	s_nop 0
	v_pk_add_f32 v[22:23], v[44:45], v[22:23]
	s_nop 0
	v_pk_add_f32 v[22:23], v[80:81], v[22:23]
	s_nop 0
	v_pk_add_f32 v[22:23], v[54:55], v[22:23]
	s_nop 0
	v_pk_add_f32 v[22:23], v[82:83], v[22:23]
	ds_bpermute_b32 v27, v48, v23
	ds_bpermute_b32 v26, v48, v22
	s_waitcnt lgkmcnt(0)
	v_pk_add_f32 v[22:23], v[22:23], v[26:27]
	ds_bpermute_b32 v27, v49, v23
	ds_bpermute_b32 v26, v49, v22
	s_waitcnt lgkmcnt(0)
	v_pk_add_f32 v[22:23], v[22:23], v[26:27]
	ds_bpermute_b32 v27, v50, v23
	ds_bpermute_b32 v26, v50, v22
	s_waitcnt lgkmcnt(0)
	v_pk_add_f32 v[22:23], v[22:23], v[26:27]
	ds_bpermute_b32 v27, v51, v23
	ds_bpermute_b32 v26, v51, v22
	s_waitcnt lgkmcnt(0)
	v_pk_add_f32 v[22:23], v[22:23], v[26:27]
	ds_bpermute_b32 v27, v52, v23
	ds_bpermute_b32 v26, v52, v22
	s_waitcnt lgkmcnt(0)
	v_pk_add_f32 v[22:23], v[22:23], v[26:27]
	ds_bpermute_b32 v27, v53, v23
	ds_bpermute_b32 v26, v53, v22
	s_waitcnt lgkmcnt(0)
	v_pk_add_f32 v[22:23], v[22:23], v[26:27]
	s_nop 0
	v_pk_fma_f32 v[26:27], v[22:23], s[2:3], v[14:15] op_sel_hi:[1,0,0]
	v_lshlrev_b64 v[22:23], 12, v[24:25]
	v_mul_f32_e32 v5, 0x4b800000, v27
	v_cmp_gt_f32_e32 vcc, s4, v27
	v_lshl_add_u64 v[44:45], v[12:13], 0, v[22:23]
	s_nop 0
	v_cndmask_b32_e32 v5, v27, v5, vcc
	v_rsq_f32_e32 v5, v5
	s_nop 0
	v_mul_f32_e32 v22, 0x45800000, v5
	v_cndmask_b32_e32 v54, v5, v22, vcc
	v_pk_mul_f32 v[24:25], v[58:59], v[54:55] op_sel_hi:[1,0]
	v_pk_mul_f32 v[22:23], v[46:47], v[54:55] op_sel_hi:[1,0]
	v_pk_mul_f32 v[46:47], v[62:63], v[54:55] op_sel_hi:[1,0]
	v_pk_mul_f32 v[56:57], v[60:61], v[54:55] op_sel_hi:[1,0]
	s_waitcnt vmcnt(0)
	v_pk_fma_f32 v[22:23], v[32:33], v[22:23], v[40:41]
	v_pk_fma_f32 v[24:25], v[34:35], v[24:25], v[42:43]
	v_pk_fma_f32 v[18:19], v[18:19], v[56:57], v[36:37]
	v_pk_fma_f32 v[20:21], v[20:21], v[46:47], v[38:39]
	global_store_dwordx4 v[44:45], v[22:25], off nt
	global_store_dwordx4 v[44:45], v[18:21], off offset:16 nt
	global_load_dwordx4 v[18:21], v[10:11], off offset:2048
	s_nop 0
	global_load_dwordx4 v[22:25], v[8:9], off offset:2048
	global_load_dwordx4 v[32:35], v[8:9], off offset:2064
	global_load_dwordx4 v[36:39], v[10:11], off offset:2064
	v_pk_mul_f32 v[40:41], v[66:67], v[54:55] op_sel_hi:[1,0]
	v_pk_mul_f32 v[42:43], v[64:65], v[54:55] op_sel_hi:[1,0]
	v_pk_mul_f32 v[46:47], v[70:71], v[54:55] op_sel_hi:[1,0]
	v_pk_mul_f32 v[54:55], v[68:69], v[54:55] op_sel_hi:[1,0]
	v_mul_f32_e32 v5, 0x4b800000, v26
	v_cmp_gt_f32_e32 vcc, s4, v26
	s_waitcnt vmcnt(2)
	v_pk_fma_f32 v[18:19], v[22:23], v[42:43], v[18:19]
	v_pk_fma_f32 v[20:21], v[24:25], v[40:41], v[20:21]
	s_waitcnt vmcnt(0)
	v_pk_fma_f32 v[22:23], v[32:33], v[54:55], v[36:37]
	v_pk_fma_f32 v[24:25], v[34:35], v[46:47], v[38:39]
	global_store_dwordx4 v[44:45], v[18:21], off offset:2048 nt
	global_store_dwordx4 v[44:45], v[22:25], off offset:2064 nt
	global_load_dwordx4 v[18:21], v[10:11], off
	s_nop 0
	global_load_dwordx4 v[22:25], v[8:9], off
	global_load_dwordx4 v[32:35], v[8:9], off offset:16
	global_load_dwordx4 v[36:39], v[10:11], off offset:16
	v_cndmask_b32_e32 v5, v26, v5, vcc
	v_rsq_f32_e32 v5, v5
	v_lshl_add_u64 v[40:41], v[12:13], 0, v[16:17]
	v_mul_f32_e32 v16, 0x45800000, v5
	v_cndmask_b32_e32 v42, v5, v16, vcc
	v_pk_mul_f32 v[26:27], v[74:75], v[42:43] op_sel_hi:[1,0]
	v_pk_mul_f32 v[16:17], v[72:73], v[42:43] op_sel_hi:[1,0]
	v_pk_mul_f32 v[44:45], v[78:79], v[42:43] op_sel_hi:[1,0]
	v_pk_mul_f32 v[46:47], v[76:77], v[42:43] op_sel_hi:[1,0]
	v_cmp_lt_i32_e32 vcc, s5, v4
	v_pk_mul_f32 v[28:29], v[28:29], v[42:43] op_sel_hi:[1,0]
	v_pk_mul_f32 v[0:1], v[0:1], v[42:43] op_sel_hi:[1,0]
	s_or_b64 s[0:1], vcc, s[0:1]
	v_pk_mul_f32 v[30:31], v[30:31], v[42:43] op_sel_hi:[1,0]
	s_waitcnt vmcnt(2)
	v_pk_fma_f32 v[16:17], v[22:23], v[16:17], v[18:19]
	v_pk_fma_f32 v[18:19], v[24:25], v[26:27], v[20:21]
	s_waitcnt vmcnt(0)
	v_pk_fma_f32 v[20:21], v[32:33], v[46:47], v[36:37]
	v_pk_fma_f32 v[22:23], v[34:35], v[44:45], v[38:39]
	global_store_dwordx4 v[40:41], v[16:19], off nt
	global_store_dwordx4 v[40:41], v[20:23], off offset:16 nt
	global_load_dwordx4 v[16:19], v[10:11], off offset:2048
	s_nop 0
	global_load_dwordx4 v[20:23], v[8:9], off offset:2048
	global_load_dwordx4 v[24:27], v[8:9], off offset:2064
	global_load_dwordx4 v[32:35], v[10:11], off offset:2064
	v_pk_mul_f32 v[36:37], v[2:3], v[42:43] op_sel_hi:[1,0]
	s_waitcnt vmcnt(2)
	v_pk_fma_f32 v[0:1], v[20:21], v[0:1], v[16:17]
	v_pk_fma_f32 v[2:3], v[22:23], v[28:29], v[18:19]
	s_waitcnt vmcnt(0)
	v_pk_fma_f32 v[16:17], v[24:25], v[36:37], v[32:33]
	v_pk_fma_f32 v[18:19], v[26:27], v[30:31], v[34:35]
	global_store_dwordx4 v[40:41], v[0:3], off offset:2048 nt
	global_store_dwordx4 v[40:41], v[16:19], off offset:2064 nt
	s_andn2_b64 exec, exec, s[0:1]
	s_cbranch_execnz .LBB0_1619
